# K-loop heads aligned to 64 bytes (s_nop padding before the loop labels) on top of the loop-edge and tight-transition variant
# speedup vs baseline: 1.0069x; 1.0012x over previous
.LBB0_1515:
	s_and_b32 s18, s6, 3
	s_lshl_b32 s12, s8, 6
	v_and_b32_e32 v19, 48, v18
	s_lshl_b32 s6, s8, 13
	v_lshlrev_b32_e32 v20, 6, v18
	s_movk_i32 s8, 0x3c0
	v_lshlrev_b32_e32 v18, 2, v18
	s_add_i32 s45, s78, 0x18000
	v_and_or_b32 v19, v20, s8, v19
	v_and_b32_e32 v18, 32, v18
	s_add_i32 s24, s45, s7
	v_bitop3_b32 v20, v19, s6, v18 bitop3:0xde
	s_lshl_b32 s6, s18, 12
	v_lshl_add_u64 v[10:11], v[10:11], 0, s[64:65]
	s_mov_b32 m0, s24
	s_add_i32 s25, s24, 0x2000
	s_add_i32 s26, s16, 0x8000
	s_add_i32 s27, s16, 0xa000
	s_waitcnt vmcnt(2)
	s_barrier
	global_load_lds_dwordx4 v[10:11], off
	v_lshl_add_u64 v[8:9], v[8:9], 0, s[64:65]
	s_mov_b32 m0, s25
	s_add_u32 s8, s2, 0x80080
	global_load_lds_dwordx4 v[8:9], off
	v_lshl_add_u64 v[6:7], v[6:7], 0, s[64:65]
	s_mov_b32 m0, s26
	s_addc_u32 s9, s3, 0
	s_add_i32 s74, s78, 0x1c000
	global_load_lds_dwordx4 v[6:7], off
	v_lshl_add_u64 v[4:5], v[4:5], 0, s[64:65]
	s_mov_b32 m0, s27
	s_add_i32 s34, s74, s7
	global_load_lds_dwordx4 v[4:5], off
	v_lshl_add_u64 v[4:5], s[8:9], 0, v[2:3]
	s_mov_b32 m0, s34
	s_add_i32 s35, s34, 0x2000
	global_load_lds_dwordx4 v[4:5], off
	v_lshl_add_u64 v[4:5], s[8:9], 0, v[136:137]
	s_mov_b32 m0, s35
	v_bitop3_b32 v142, v19, s6, v18 bitop3:0xde
	global_load_lds_dwordx4 v[4:5], off
	v_readlane_b32 s6, v254, 32
	v_lshlrev_b32_e32 v4, 15, v12
	v_readlane_b32 s7, v254, 33
	s_add_u32 s37, s38, s6
	v_and_b32_e32 v4, 0xffff0000, v4
	s_addc_u32 s40, s39, s7
	v_readlane_b32 s6, v254, 31
	v_lshl_add_u32 v4, v13, 12, v4
	v_and_b32_e32 v5, 1, v12
	s_add_u32 s6, s38, s6
	v_readlane_b32 s7, v254, 34
	v_lshl_or_b32 v4, v5, 6, v4
	s_addc_u32 s7, s39, s7
	v_lshl_add_u32 v4, v14, 1, v4
	v_mov_b32_e32 v5, v3
	v_lshl_add_u64 v[138:139], s[6:7], 0, v[4:5]
	v_lshlrev_b32_e32 v4, 15, v15
	v_and_b32_e32 v4, 0xffff0000, v4
	v_lshl_add_u32 v4, v16, 12, v4
	v_and_b32_e32 v5, 1, v15
	v_lshl_or_b32 v4, v5, 6, v4
	v_lshl_add_u32 v4, v17, 1, v4
	v_mov_b32_e32 v5, v3
	s_waitcnt vmcnt(6)
	v_lshl_add_u64 v[140:141], s[6:7], 0, v[4:5]
	v_readlane_b32 s6, v254, 37
	s_add_u32 s41, s38, s6
	v_readlane_b32 s6, v254, 56
	v_mov_b32_e32 v4, 0
	v_readlane_b32 s50, v253, 16
	s_mov_b32 s67, s36
	s_addc_u32 s42, s39, s6
	s_mov_b32 s43, -2
	s_mov_b64 s[6:7], 0
	v_add_u32_e32 v143, s78, v20
	v_mov_b32_e32 v5, v4
	v_mov_b32_e32 v6, v4
	v_mov_b32_e32 v7, v4
	v_mov_b32_e32 v8, v4
	v_mov_b32_e32 v9, v4
	v_mov_b32_e32 v10, v4
	v_mov_b32_e32 v11, v4
	v_mov_b32_e32 v20, v4
	v_mov_b32_e32 v21, v4
	v_mov_b32_e32 v22, v4
	v_mov_b32_e32 v23, v4
	v_mov_b32_e32 v24, v4
	v_mov_b32_e32 v25, v4
	v_mov_b32_e32 v26, v4
	v_mov_b32_e32 v27, v4
	v_mov_b32_e32 v36, v4
	v_mov_b32_e32 v37, v4
	v_mov_b32_e32 v38, v4
	v_mov_b32_e32 v39, v4
	v_mov_b32_e32 v40, v4
	v_mov_b32_e32 v41, v4
	v_mov_b32_e32 v42, v4
	v_mov_b32_e32 v43, v4
	v_mov_b32_e32 v52, v4
	v_mov_b32_e32 v53, v4
	v_mov_b32_e32 v54, v4
	v_mov_b32_e32 v55, v4
	v_mov_b32_e32 v56, v4
	v_mov_b32_e32 v57, v4
	v_mov_b32_e32 v58, v4
	v_mov_b32_e32 v59, v4
	v_mov_b32_e32 v12, v4
	v_mov_b32_e32 v13, v4
	v_mov_b32_e32 v14, v4
	v_mov_b32_e32 v15, v4
	v_mov_b32_e32 v16, v4
	v_mov_b32_e32 v17, v4
	v_mov_b32_e32 v18, v4
	v_mov_b32_e32 v19, v4
	v_mov_b32_e32 v28, v4
	v_mov_b32_e32 v29, v4
	v_mov_b32_e32 v30, v4
	v_mov_b32_e32 v31, v4
	v_mov_b32_e32 v32, v4
	v_mov_b32_e32 v33, v4
	v_mov_b32_e32 v34, v4
	v_mov_b32_e32 v35, v4
	v_mov_b32_e32 v44, v4
	v_mov_b32_e32 v45, v4
	v_mov_b32_e32 v46, v4
	v_mov_b32_e32 v47, v4
	v_mov_b32_e32 v48, v4
	v_mov_b32_e32 v49, v4
	v_mov_b32_e32 v50, v4
	v_mov_b32_e32 v51, v4
	v_mov_b32_e32 v60, v4
	v_mov_b32_e32 v61, v4
	v_mov_b32_e32 v62, v4
	v_mov_b32_e32 v63, v4
	v_mov_b32_e32 v64, v4
	v_mov_b32_e32 v65, v4
	v_mov_b32_e32 v66, v4
	v_mov_b32_e32 v67, v4
	v_mov_b32_e32 v68, v4
	v_mov_b32_e32 v69, v4
	v_mov_b32_e32 v70, v4
	v_mov_b32_e32 v71, v4
	v_mov_b32_e32 v72, v4
	v_mov_b32_e32 v73, v4
	v_mov_b32_e32 v74, v4
	v_mov_b32_e32 v75, v4
	v_mov_b32_e32 v84, v4
	v_mov_b32_e32 v85, v4
	v_mov_b32_e32 v86, v4
	v_mov_b32_e32 v87, v4
	v_mov_b32_e32 v88, v4
	v_mov_b32_e32 v89, v4
	v_mov_b32_e32 v90, v4
	v_mov_b32_e32 v91, v4
	v_mov_b32_e32 v100, v4
	v_mov_b32_e32 v101, v4
	v_mov_b32_e32 v102, v4
	v_mov_b32_e32 v103, v4
	v_mov_b32_e32 v104, v4
	v_mov_b32_e32 v105, v4
	v_mov_b32_e32 v106, v4
	v_mov_b32_e32 v107, v4
	v_mov_b32_e32 v116, v4
	v_mov_b32_e32 v117, v4
	v_mov_b32_e32 v118, v4
	v_mov_b32_e32 v119, v4
	v_mov_b32_e32 v120, v4
	v_mov_b32_e32 v121, v4
	v_mov_b32_e32 v122, v4
	v_mov_b32_e32 v123, v4
	v_mov_b32_e32 v76, v4
	v_mov_b32_e32 v77, v4
	v_mov_b32_e32 v78, v4
	v_mov_b32_e32 v79, v4
	v_mov_b32_e32 v80, v4
	v_mov_b32_e32 v81, v4
	v_mov_b32_e32 v82, v4
	v_mov_b32_e32 v83, v4
	v_mov_b32_e32 v92, v4
	v_mov_b32_e32 v93, v4
	v_mov_b32_e32 v94, v4
	v_mov_b32_e32 v95, v4
	v_mov_b32_e32 v96, v4
	v_mov_b32_e32 v97, v4
	v_mov_b32_e32 v98, v4
	v_mov_b32_e32 v99, v4
	v_mov_b32_e32 v108, v4
	v_mov_b32_e32 v109, v4
	v_mov_b32_e32 v110, v4
	v_mov_b32_e32 v111, v4
	v_mov_b32_e32 v112, v4
	v_mov_b32_e32 v113, v4
	v_mov_b32_e32 v114, v4
	v_mov_b32_e32 v115, v4
	v_mov_b32_e32 v124, v4
	v_mov_b32_e32 v125, v4
	v_mov_b32_e32 v126, v4
	v_mov_b32_e32 v127, v4
	v_mov_b32_e32 v128, v4
	v_mov_b32_e32 v129, v4
	v_mov_b32_e32 v130, v4
	v_mov_b32_e32 v131, v4
	v_readlane_b32 s58, v253, 62
	v_readlane_b32 s48, v254, 57
	v_readlane_b32 s51, v253, 17
	v_readlane_b32 s73, v254, 13
	s_mov_b32 s49, 0x38400000
	s_barrier
	v_readlane_b32 s59, v253, 63
	s_nop 0
	s_cmp_eq_u32 s48, 13
	s_cselect_b32 s100, 1, 0
	s_bfe_u32 s101, s21, 0x20006
	s_cmp_gt_u32 s101, 1
	s_cselect_b32 s101, s100, 0
	.p2alignl 6, 3212836864

.LBB0_1874:
	s_and_b64 s[34:35], s[40:41], exec
	v_mov_b32_e32 v123, 0
	s_cselect_b32 s35, s9, s43
	s_cselect_b32 s34, s8, s42
	s_andn2_b64 vcc, exec, s[12:13]
	v_mov_b32_e32 v122, v123
	v_mov_b32_e32 v121, v123
	v_mov_b32_e32 v120, v123
	v_mov_b32_e32 v131, v123
	v_mov_b32_e32 v130, v123
	v_mov_b32_e32 v129, v123
	v_mov_b32_e32 v128, v123
	v_mov_b32_e32 v115, v123
	v_mov_b32_e32 v114, v123
	v_mov_b32_e32 v113, v123
	v_mov_b32_e32 v112, v123
	v_mov_b32_e32 v111, v123
	v_mov_b32_e32 v110, v123
	v_mov_b32_e32 v109, v123
	v_mov_b32_e32 v108, v123
	v_mov_b32_e32 v99, v123
	v_mov_b32_e32 v98, v123
	v_mov_b32_e32 v97, v123
	v_mov_b32_e32 v96, v123
	v_mov_b32_e32 v95, v123
	v_mov_b32_e32 v94, v123
	v_mov_b32_e32 v93, v123
	v_mov_b32_e32 v92, v123
	v_mov_b32_e32 v83, v123
	v_mov_b32_e32 v82, v123
	v_mov_b32_e32 v81, v123
	v_mov_b32_e32 v80, v123
	v_mov_b32_e32 v79, v123
	v_mov_b32_e32 v78, v123
	v_mov_b32_e32 v77, v123
	v_mov_b32_e32 v76, v123
	v_mov_b32_e32 v127, v123
	v_mov_b32_e32 v126, v123
	v_mov_b32_e32 v125, v123
	v_mov_b32_e32 v124, v123
	v_mov_b32_e32 v119, v123
	v_mov_b32_e32 v118, v123
	v_mov_b32_e32 v117, v123
	v_mov_b32_e32 v116, v123
	v_mov_b32_e32 v107, v123
	v_mov_b32_e32 v106, v123
	v_mov_b32_e32 v105, v123
	v_mov_b32_e32 v104, v123
	v_mov_b32_e32 v103, v123
	v_mov_b32_e32 v102, v123
	v_mov_b32_e32 v101, v123
	v_mov_b32_e32 v100, v123
	v_mov_b32_e32 v91, v123
	v_mov_b32_e32 v90, v123
	v_mov_b32_e32 v89, v123
	v_mov_b32_e32 v88, v123
	v_mov_b32_e32 v87, v123
	v_mov_b32_e32 v86, v123
	v_mov_b32_e32 v85, v123
	v_mov_b32_e32 v84, v123
	v_mov_b32_e32 v75, v123
	v_mov_b32_e32 v74, v123
	v_mov_b32_e32 v73, v123
	v_mov_b32_e32 v72, v123
	v_mov_b32_e32 v71, v123
	v_mov_b32_e32 v70, v123
	v_mov_b32_e32 v69, v123
	v_mov_b32_e32 v68, v123
	v_mov_b32_e32 v67, v123
	v_mov_b32_e32 v66, v123
	v_mov_b32_e32 v65, v123
	v_mov_b32_e32 v64, v123
	v_mov_b32_e32 v63, v123
	v_mov_b32_e32 v62, v123
	v_mov_b32_e32 v61, v123
	v_mov_b32_e32 v60, v123
	v_mov_b32_e32 v51, v123
	v_mov_b32_e32 v50, v123
	v_mov_b32_e32 v49, v123
	v_mov_b32_e32 v48, v123
	v_mov_b32_e32 v47, v123
	v_mov_b32_e32 v46, v123
	v_mov_b32_e32 v45, v123
	v_mov_b32_e32 v44, v123
	v_mov_b32_e32 v35, v123
	v_mov_b32_e32 v34, v123
	v_mov_b32_e32 v33, v123
	v_mov_b32_e32 v32, v123
	v_mov_b32_e32 v31, v123
	v_mov_b32_e32 v30, v123
	v_mov_b32_e32 v29, v123
	v_mov_b32_e32 v28, v123
	v_mov_b32_e32 v19, v123
	v_mov_b32_e32 v18, v123
	v_mov_b32_e32 v17, v123
	v_mov_b32_e32 v16, v123
	v_mov_b32_e32 v15, v123
	v_mov_b32_e32 v14, v123
	v_mov_b32_e32 v13, v123
	v_mov_b32_e32 v12, v123
	v_mov_b32_e32 v59, v123
	v_mov_b32_e32 v58, v123
	v_mov_b32_e32 v57, v123
	v_mov_b32_e32 v56, v123
	v_mov_b32_e32 v55, v123
	v_mov_b32_e32 v54, v123
	v_mov_b32_e32 v53, v123
	v_mov_b32_e32 v52, v123
	v_mov_b32_e32 v43, v123
	v_mov_b32_e32 v42, v123
	v_mov_b32_e32 v41, v123
	v_mov_b32_e32 v40, v123
	v_mov_b32_e32 v39, v123
	v_mov_b32_e32 v38, v123
	v_mov_b32_e32 v37, v123
	v_mov_b32_e32 v36, v123
	v_mov_b32_e32 v27, v123
	v_mov_b32_e32 v26, v123
	v_mov_b32_e32 v25, v123
	v_mov_b32_e32 v24, v123
	v_mov_b32_e32 v23, v123
	v_mov_b32_e32 v22, v123
	v_mov_b32_e32 v21, v123
	v_mov_b32_e32 v20, v123
	v_mov_b32_e32 v11, v123
	v_mov_b32_e32 v10, v123
	v_mov_b32_e32 v9, v123
	v_mov_b32_e32 v8, v123
	v_mov_b32_e32 v7, v123
	v_mov_b32_e32 v6, v123
	v_mov_b32_e32 v5, v123
	v_mov_b32_e32 v4, v123
	s_cbranch_vccnz .LBB0_1877
	s_add_u32 s42, s42, 0x80
	s_addc_u32 s43, s43, 0
	s_add_u32 s68, s18, 0x100
	v_mov_b32_e32 v4, 0
	s_addc_u32 s69, s19, 0
	s_mov_b32 s18, 0
	v_mov_b32_e32 v5, v4
	v_mov_b32_e32 v6, v4
	v_mov_b32_e32 v7, v4
	v_mov_b32_e32 v8, v4
	v_mov_b32_e32 v9, v4
	v_mov_b32_e32 v10, v4
	v_mov_b32_e32 v11, v4
	v_mov_b32_e32 v20, v4
	v_mov_b32_e32 v21, v4
	v_mov_b32_e32 v22, v4
	v_mov_b32_e32 v23, v4
	v_mov_b32_e32 v24, v4
	v_mov_b32_e32 v25, v4
	v_mov_b32_e32 v26, v4
	v_mov_b32_e32 v27, v4
	v_mov_b32_e32 v36, v4
	v_mov_b32_e32 v37, v4
	v_mov_b32_e32 v38, v4
	v_mov_b32_e32 v39, v4
	v_mov_b32_e32 v40, v4
	v_mov_b32_e32 v41, v4
	v_mov_b32_e32 v42, v4
	v_mov_b32_e32 v43, v4
	v_mov_b32_e32 v52, v4
	v_mov_b32_e32 v53, v4
	v_mov_b32_e32 v54, v4
	v_mov_b32_e32 v55, v4
	v_mov_b32_e32 v56, v4
	v_mov_b32_e32 v57, v4
	v_mov_b32_e32 v58, v4
	v_mov_b32_e32 v59, v4
	v_mov_b32_e32 v12, v4
	v_mov_b32_e32 v13, v4
	v_mov_b32_e32 v14, v4
	v_mov_b32_e32 v15, v4
	v_mov_b32_e32 v16, v4
	v_mov_b32_e32 v17, v4
	v_mov_b32_e32 v18, v4
	v_mov_b32_e32 v19, v4
	v_mov_b32_e32 v28, v4
	v_mov_b32_e32 v29, v4
	v_mov_b32_e32 v30, v4
	v_mov_b32_e32 v31, v4
	v_mov_b32_e32 v32, v4
	v_mov_b32_e32 v33, v4
	v_mov_b32_e32 v34, v4
	v_mov_b32_e32 v35, v4
	v_mov_b32_e32 v44, v4
	v_mov_b32_e32 v45, v4
	v_mov_b32_e32 v46, v4
	v_mov_b32_e32 v47, v4
	v_mov_b32_e32 v48, v4
	v_mov_b32_e32 v49, v4
	v_mov_b32_e32 v50, v4
	v_mov_b32_e32 v51, v4
	v_mov_b32_e32 v60, v4
	v_mov_b32_e32 v61, v4
	v_mov_b32_e32 v62, v4
	v_mov_b32_e32 v63, v4
	v_mov_b32_e32 v64, v4
	v_mov_b32_e32 v65, v4
	v_mov_b32_e32 v66, v4
	v_mov_b32_e32 v67, v4
	v_mov_b32_e32 v68, v4
	v_mov_b32_e32 v69, v4
	v_mov_b32_e32 v70, v4
	v_mov_b32_e32 v71, v4
	v_mov_b32_e32 v72, v4
	v_mov_b32_e32 v73, v4
	v_mov_b32_e32 v74, v4
	v_mov_b32_e32 v75, v4
	v_mov_b32_e32 v84, v4
	v_mov_b32_e32 v85, v4
	v_mov_b32_e32 v86, v4
	v_mov_b32_e32 v87, v4
	v_mov_b32_e32 v88, v4
	v_mov_b32_e32 v89, v4
	v_mov_b32_e32 v90, v4
	v_mov_b32_e32 v91, v4
	v_mov_b32_e32 v100, v4
	v_mov_b32_e32 v101, v4
	v_mov_b32_e32 v102, v4
	v_mov_b32_e32 v103, v4
	v_mov_b32_e32 v104, v4
	v_mov_b32_e32 v105, v4
	v_mov_b32_e32 v106, v4
	v_mov_b32_e32 v107, v4
	v_mov_b32_e32 v116, v4
	v_mov_b32_e32 v117, v4
	v_mov_b32_e32 v118, v4
	v_mov_b32_e32 v119, v4
	v_mov_b32_e32 v124, v4
	v_mov_b32_e32 v125, v4
	v_mov_b32_e32 v126, v4
	v_mov_b32_e32 v127, v4
	v_mov_b32_e32 v76, v4
	v_mov_b32_e32 v77, v4
	v_mov_b32_e32 v78, v4
	v_mov_b32_e32 v79, v4
	v_mov_b32_e32 v80, v4
	v_mov_b32_e32 v81, v4
	v_mov_b32_e32 v82, v4
	v_mov_b32_e32 v83, v4
	v_mov_b32_e32 v92, v4
	v_mov_b32_e32 v93, v4
	v_mov_b32_e32 v94, v4
	v_mov_b32_e32 v95, v4
	v_mov_b32_e32 v96, v4
	v_mov_b32_e32 v97, v4
	v_mov_b32_e32 v98, v4
	v_mov_b32_e32 v99, v4
	v_mov_b32_e32 v108, v4
	v_mov_b32_e32 v109, v4
	v_mov_b32_e32 v110, v4
	v_mov_b32_e32 v111, v4
	v_mov_b32_e32 v112, v4
	v_mov_b32_e32 v113, v4
	v_mov_b32_e32 v114, v4
	v_mov_b32_e32 v115, v4
	v_mov_b32_e32 v128, v4
	v_mov_b32_e32 v129, v4
	v_mov_b32_e32 v130, v4
	v_mov_b32_e32 v131, v4
	v_mov_b32_e32 v120, v4
	v_mov_b32_e32 v121, v4
	v_mov_b32_e32 v122, v4
	v_mov_b32_e32 v123, v4
	.p2alignl 6, 3212836864

.LBB0_1890:
	s_ashr_i32 s59, s58, 31
	s_lshl_b64 s[14:15], s[58:59], 19
	s_add_u32 s76, s97, s14
	s_addc_u32 s77, s21, s15
	s_and_b64 s[14:15], s[12:13], exec
	s_cselect_b32 s3, s77, s9
	s_cselect_b32 s14, s76, s8
	s_ashr_i32 s89, s88, 31
	s_lshl_b64 s[18:19], s[88:89], 19
	s_add_u32 s34, s53, s18
	s_addc_u32 s35, s79, s19
	s_and_b64 s[12:13], s[12:13], exec
	s_cselect_b32 s15, s35, s11
	s_cselect_b32 s18, s34, s10
	s_add_u32 s8, s8, 0x40080
	s_addc_u32 s9, s9, 0
	s_add_u32 s19, s10, 0x100
	v_mov_b32_e32 v36, 0
	s_addc_u32 s24, s11, 0
	s_mov_b32 s25, -2
	v_mov_b32_e32 v37, v36
	v_mov_b32_e32 v38, v36
	v_mov_b32_e32 v39, v36
	v_mov_b32_e32 v40, v36
	v_mov_b32_e32 v41, v36
	v_mov_b32_e32 v42, v36
	v_mov_b32_e32 v43, v36
	v_mov_b32_e32 v52, v36
	v_mov_b32_e32 v53, v36
	v_mov_b32_e32 v54, v36
	v_mov_b32_e32 v55, v36
	v_mov_b32_e32 v56, v36
	v_mov_b32_e32 v57, v36
	v_mov_b32_e32 v58, v36
	v_mov_b32_e32 v59, v36
	v_mov_b32_e32 v68, v36
	v_mov_b32_e32 v69, v36
	v_mov_b32_e32 v70, v36
	v_mov_b32_e32 v71, v36
	v_mov_b32_e32 v72, v36
	v_mov_b32_e32 v73, v36
	v_mov_b32_e32 v74, v36
	v_mov_b32_e32 v75, v36
	v_mov_b32_e32 v84, v36
	v_mov_b32_e32 v85, v36
	v_mov_b32_e32 v86, v36
	v_mov_b32_e32 v87, v36
	v_mov_b32_e32 v88, v36
	v_mov_b32_e32 v89, v36
	v_mov_b32_e32 v90, v36
	v_mov_b32_e32 v91, v36
	v_mov_b32_e32 v44, v36
	v_mov_b32_e32 v45, v36
	v_mov_b32_e32 v46, v36
	v_mov_b32_e32 v47, v36
	v_mov_b32_e32 v48, v36
	v_mov_b32_e32 v49, v36
	v_mov_b32_e32 v50, v36
	v_mov_b32_e32 v51, v36
	v_mov_b32_e32 v60, v36
	v_mov_b32_e32 v61, v36
	v_mov_b32_e32 v62, v36
	v_mov_b32_e32 v63, v36
	v_mov_b32_e32 v64, v36
	v_mov_b32_e32 v65, v36
	v_mov_b32_e32 v66, v36
	v_mov_b32_e32 v67, v36
	v_mov_b32_e32 v76, v36
	v_mov_b32_e32 v77, v36
	v_mov_b32_e32 v78, v36
	v_mov_b32_e32 v79, v36
	v_mov_b32_e32 v80, v36
	v_mov_b32_e32 v81, v36
	v_mov_b32_e32 v82, v36
	v_mov_b32_e32 v83, v36
	v_mov_b32_e32 v92, v36
	v_mov_b32_e32 v93, v36
	v_mov_b32_e32 v94, v36
	v_mov_b32_e32 v95, v36
	v_mov_b32_e32 v96, v36
	v_mov_b32_e32 v97, v36
	v_mov_b32_e32 v98, v36
	v_mov_b32_e32 v99, v36
	v_mov_b32_e32 v100, v36
	v_mov_b32_e32 v101, v36
	v_mov_b32_e32 v102, v36
	v_mov_b32_e32 v103, v36
	v_mov_b32_e32 v104, v36
	v_mov_b32_e32 v105, v36
	v_mov_b32_e32 v106, v36
	v_mov_b32_e32 v107, v36
	v_mov_b32_e32 v116, v36
	v_mov_b32_e32 v117, v36
	v_mov_b32_e32 v118, v36
	v_mov_b32_e32 v119, v36
	v_mov_b32_e32 v120, v36
	v_mov_b32_e32 v121, v36
	v_mov_b32_e32 v122, v36
	v_mov_b32_e32 v123, v36
	v_mov_b32_e32 v132, v36
	v_mov_b32_e32 v133, v36
	v_mov_b32_e32 v134, v36
	v_mov_b32_e32 v135, v36
	v_mov_b32_e32 v136, v36
	v_mov_b32_e32 v137, v36
	v_mov_b32_e32 v138, v36
	v_mov_b32_e32 v139, v36
	v_mov_b32_e32 v148, v36
	v_mov_b32_e32 v149, v36
	v_mov_b32_e32 v150, v36
	v_mov_b32_e32 v151, v36
	v_mov_b32_e32 v152, v36
	v_mov_b32_e32 v153, v36
	v_mov_b32_e32 v154, v36
	v_mov_b32_e32 v155, v36
	v_mov_b32_e32 v108, v36
	v_mov_b32_e32 v109, v36
	v_mov_b32_e32 v110, v36
	v_mov_b32_e32 v111, v36
	v_mov_b32_e32 v112, v36
	v_mov_b32_e32 v113, v36
	v_mov_b32_e32 v114, v36
	v_mov_b32_e32 v115, v36
	v_mov_b32_e32 v124, v36
	v_mov_b32_e32 v125, v36
	v_mov_b32_e32 v126, v36
	v_mov_b32_e32 v127, v36
	v_mov_b32_e32 v128, v36
	v_mov_b32_e32 v129, v36
	v_mov_b32_e32 v130, v36
	v_mov_b32_e32 v131, v36
	v_mov_b32_e32 v140, v36
	v_mov_b32_e32 v141, v36
	v_mov_b32_e32 v142, v36
	v_mov_b32_e32 v143, v36
	v_mov_b32_e32 v144, v36
	v_mov_b32_e32 v145, v36
	v_mov_b32_e32 v146, v36
	v_mov_b32_e32 v147, v36
	v_mov_b32_e32 v156, v36
	v_mov_b32_e32 v157, v36
	v_mov_b32_e32 v158, v36
	v_mov_b32_e32 v159, v36
	v_mov_b32_e32 v160, v36
	v_mov_b32_e32 v161, v36
	v_mov_b32_e32 v162, v36
	v_mov_b32_e32 v163, v36
	.p2alignl 6, 3212836864

.LBB0_2327:
	v_lshl_add_u64 v[4:5], s[4:5], 0, v[2:3]
	v_mov_b32_e32 v137, v3
	s_add_i32 s26, s45, s37
	v_lshl_add_u64 v[6:7], s[4:5], 0, v[136:137]
	v_mov_b32_e32 v133, v3
	v_lshl_add_u64 v[4:5], v[4:5], 0, s[64:65]
	s_mov_b32 m0, s26
	s_add_i32 s27, s26, 0x2000
	v_lshl_add_u64 v[12:13], s[6:7], 0, v[132:133]
	v_mov_b32_e32 v135, v3
	s_waitcnt vmcnt(2)
	s_barrier
	global_load_lds_dwordx4 v[4:5], off
	v_lshl_add_u64 v[4:5], v[6:7], 0, s[64:65]
	s_mov_b32 m0, s27
	s_add_i32 s34, s22, 0x8000
	v_lshl_add_u64 v[14:15], s[6:7], 0, v[134:135]
	global_load_lds_dwordx4 v[4:5], off
	v_lshl_add_u64 v[4:5], v[12:13], 0, s[64:65]
	s_mov_b32 m0, s34
	s_add_i32 s35, s22, 0xa000
	v_lshl_add_u64 v[8:9], s[10:11], 0, v[2:3]
	global_load_lds_dwordx4 v[4:5], off
	v_lshl_add_u64 v[4:5], v[14:15], 0, s[64:65]
	s_mov_b32 m0, s35
	s_add_i32 s37, s74, s37
	v_lshl_add_u64 v[10:11], s[10:11], 0, v[136:137]
	global_load_lds_dwordx4 v[4:5], off
	v_lshl_add_u64 v[4:5], v[8:9], 0, s[64:65]
	s_mov_b32 m0, s37
	s_add_i32 s40, s37, 0x2000
	global_load_lds_dwordx4 v[4:5], off
	v_lshl_add_u64 v[4:5], v[10:11], 0, s[64:65]
	s_mov_b32 m0, s40
	s_lshl_b32 s10, s13, 5
	global_load_lds_dwordx4 v[4:5], off
	s_waitcnt vmcnt(6)
	s_lshl_b32 s15, s12, 6
	s_and_b32 s16, s10, 0x60
	v_mov_b32_e32 v127, 0
	s_cmp_lt_i32 s8, 64
	v_mov_b32_e32 v126, v127
	v_mov_b32_e32 v125, v127
	v_mov_b32_e32 v124, v127
	v_mov_b32_e32 v131, v127
	v_mov_b32_e32 v130, v127
	v_mov_b32_e32 v129, v127
	v_mov_b32_e32 v128, v127
	v_mov_b32_e32 v115, v127
	v_mov_b32_e32 v114, v127
	v_mov_b32_e32 v113, v127
	v_mov_b32_e32 v112, v127
	v_mov_b32_e32 v111, v127
	v_mov_b32_e32 v110, v127
	v_mov_b32_e32 v109, v127
	v_mov_b32_e32 v108, v127
	v_mov_b32_e32 v99, v127
	v_mov_b32_e32 v98, v127
	v_mov_b32_e32 v97, v127
	v_mov_b32_e32 v96, v127
	v_mov_b32_e32 v95, v127
	v_mov_b32_e32 v94, v127
	v_mov_b32_e32 v93, v127
	v_mov_b32_e32 v92, v127
	v_mov_b32_e32 v83, v127
	v_mov_b32_e32 v82, v127
	v_mov_b32_e32 v81, v127
	v_mov_b32_e32 v80, v127
	v_mov_b32_e32 v79, v127
	v_mov_b32_e32 v78, v127
	v_mov_b32_e32 v77, v127
	v_mov_b32_e32 v76, v127
	v_mov_b32_e32 v123, v127
	v_mov_b32_e32 v122, v127
	v_mov_b32_e32 v121, v127
	v_mov_b32_e32 v120, v127
	v_mov_b32_e32 v119, v127
	v_mov_b32_e32 v118, v127
	v_mov_b32_e32 v117, v127
	v_mov_b32_e32 v116, v127
	v_mov_b32_e32 v107, v127
	v_mov_b32_e32 v106, v127
	v_mov_b32_e32 v105, v127
	v_mov_b32_e32 v104, v127
	v_mov_b32_e32 v103, v127
	v_mov_b32_e32 v102, v127
	v_mov_b32_e32 v101, v127
	v_mov_b32_e32 v100, v127
	v_mov_b32_e32 v91, v127
	v_mov_b32_e32 v90, v127
	v_mov_b32_e32 v89, v127
	v_mov_b32_e32 v88, v127
	v_mov_b32_e32 v87, v127
	v_mov_b32_e32 v86, v127
	v_mov_b32_e32 v85, v127
	v_mov_b32_e32 v84, v127
	v_mov_b32_e32 v75, v127
	v_mov_b32_e32 v74, v127
	v_mov_b32_e32 v73, v127
	v_mov_b32_e32 v72, v127
	v_mov_b32_e32 v71, v127
	v_mov_b32_e32 v70, v127
	v_mov_b32_e32 v69, v127
	v_mov_b32_e32 v68, v127
	v_mov_b32_e32 v67, v127
	v_mov_b32_e32 v66, v127
	v_mov_b32_e32 v65, v127
	v_mov_b32_e32 v64, v127
	v_mov_b32_e32 v63, v127
	v_mov_b32_e32 v62, v127
	v_mov_b32_e32 v61, v127
	v_mov_b32_e32 v60, v127
	v_mov_b32_e32 v51, v127
	v_mov_b32_e32 v50, v127
	v_mov_b32_e32 v49, v127
	v_mov_b32_e32 v48, v127
	v_mov_b32_e32 v47, v127
	v_mov_b32_e32 v46, v127
	v_mov_b32_e32 v45, v127
	v_mov_b32_e32 v44, v127
	v_mov_b32_e32 v35, v127
	v_mov_b32_e32 v34, v127
	v_mov_b32_e32 v33, v127
	v_mov_b32_e32 v32, v127
	v_mov_b32_e32 v31, v127
	v_mov_b32_e32 v30, v127
	v_mov_b32_e32 v29, v127
	v_mov_b32_e32 v28, v127
	v_mov_b32_e32 v19, v127
	v_mov_b32_e32 v18, v127
	v_mov_b32_e32 v17, v127
	v_mov_b32_e32 v16, v127
	v_mov_b32_e32 v15, v127
	v_mov_b32_e32 v14, v127
	v_mov_b32_e32 v13, v127
	v_mov_b32_e32 v12, v127
	v_mov_b32_e32 v59, v127
	v_mov_b32_e32 v58, v127
	v_mov_b32_e32 v57, v127
	v_mov_b32_e32 v56, v127
	v_mov_b32_e32 v55, v127
	v_mov_b32_e32 v54, v127
	v_mov_b32_e32 v53, v127
	v_mov_b32_e32 v52, v127
	v_mov_b32_e32 v43, v127
	v_mov_b32_e32 v42, v127
	v_mov_b32_e32 v41, v127
	v_mov_b32_e32 v40, v127
	v_mov_b32_e32 v39, v127
	v_mov_b32_e32 v38, v127
	v_mov_b32_e32 v37, v127
	v_mov_b32_e32 v36, v127
	v_mov_b32_e32 v27, v127
	v_mov_b32_e32 v26, v127
	v_mov_b32_e32 v25, v127
	v_mov_b32_e32 v24, v127
	v_mov_b32_e32 v23, v127
	v_mov_b32_e32 v22, v127
	v_mov_b32_e32 v21, v127
	v_mov_b32_e32 v20, v127
	v_mov_b32_e32 v11, v127
	v_mov_b32_e32 v10, v127
	v_mov_b32_e32 v9, v127
	v_mov_b32_e32 v8, v127
	v_mov_b32_e32 v7, v127
	v_mov_b32_e32 v6, v127
	v_mov_b32_e32 v5, v127
	v_mov_b32_e32 v4, v127
	s_barrier
	s_cbranch_scc1 .LBB0_2330
	s_lshr_b32 s9, s9, 26
	v_and_b32_e32 v4, 15, v138
	s_add_i32 s9, s8, s9
	v_or_b32_e32 v5, s15, v4
	s_ashr_i32 s41, s9, 6
	v_and_b32_e32 v6, 48, v138
	v_lshlrev_b32_e32 v7, 6, v5
	s_movk_i32 s9, 0x3c0
	v_lshlrev_b32_e32 v5, 2, v5
	v_and_or_b32 v7, v7, s9, v6
	s_lshl_b32 s9, s12, 13
	v_and_b32_e32 v5, 32, v5
	v_bitop3_b32 v7, v7, s9, v5 bitop3:0xde
	v_lshlrev_b32_e32 v5, 2, v138
	v_lshl_or_b32 v4, v4, 6, v6
	s_lshl_b32 s9, s16, 7
	v_and_b32_e32 v5, 32, v5
	v_readlane_b32 s10, v254, 35
	s_add_i32 s42, s41, -2
	v_bitop3_b32 v142, s9, v4, v5 bitop3:0xf6
	s_mul_hi_i32 s9, s10, s8
	s_mul_i32 s8, s10, s8
	v_readlane_b32 s10, v254, 59
	v_readlane_b32 s11, v254, 60
	s_add_u32 s8, s10, s8
	s_addc_u32 s9, s11, s9
	v_add_u32_e32 v4, v141, v139
	s_add_u32 s8, s38, s8
	v_add_lshl_u32 v4, v4, v140, 1
	v_mov_b32_e32 v5, v3
	s_addc_u32 s9, s39, s9
	v_lshl_add_u64 v[138:139], s[8:9], 0, v[4:5]
	v_add_u32_e32 v4, v145, v143
	v_add_lshl_u32 v4, v4, v144, 1
	v_lshl_add_u64 v[140:141], s[8:9], 0, v[4:5]
	v_mov_b32_e32 v4, 0
	s_mov_b32 s12, 0
	s_mov_b64 s[8:9], 0
	v_add_u32_e32 v143, s43, v7
	v_mov_b32_e32 v5, v4
	v_mov_b32_e32 v6, v4
	v_mov_b32_e32 v7, v4
	v_mov_b32_e32 v8, v4
	v_mov_b32_e32 v9, v4
	v_mov_b32_e32 v10, v4
	v_mov_b32_e32 v11, v4
	v_mov_b32_e32 v20, v4
	v_mov_b32_e32 v21, v4
	v_mov_b32_e32 v22, v4
	v_mov_b32_e32 v23, v4
	v_mov_b32_e32 v24, v4
	v_mov_b32_e32 v25, v4
	v_mov_b32_e32 v26, v4
	v_mov_b32_e32 v27, v4
	v_mov_b32_e32 v36, v4
	v_mov_b32_e32 v37, v4
	v_mov_b32_e32 v38, v4
	v_mov_b32_e32 v39, v4
	v_mov_b32_e32 v40, v4
	v_mov_b32_e32 v41, v4
	v_mov_b32_e32 v42, v4
	v_mov_b32_e32 v43, v4
	v_mov_b32_e32 v52, v4
	v_mov_b32_e32 v53, v4
	v_mov_b32_e32 v54, v4
	v_mov_b32_e32 v55, v4
	v_mov_b32_e32 v56, v4
	v_mov_b32_e32 v57, v4
	v_mov_b32_e32 v58, v4
	v_mov_b32_e32 v59, v4
	v_mov_b32_e32 v12, v4
	v_mov_b32_e32 v13, v4
	v_mov_b32_e32 v14, v4
	v_mov_b32_e32 v15, v4
	v_mov_b32_e32 v16, v4
	v_mov_b32_e32 v17, v4
	v_mov_b32_e32 v18, v4
	v_mov_b32_e32 v19, v4
	v_mov_b32_e32 v28, v4
	v_mov_b32_e32 v29, v4
	v_mov_b32_e32 v30, v4
	v_mov_b32_e32 v31, v4
	v_mov_b32_e32 v32, v4
	v_mov_b32_e32 v33, v4
	v_mov_b32_e32 v34, v4
	v_mov_b32_e32 v35, v4
	v_mov_b32_e32 v44, v4
	v_mov_b32_e32 v45, v4
	v_mov_b32_e32 v46, v4
	v_mov_b32_e32 v47, v4
	v_mov_b32_e32 v48, v4
	v_mov_b32_e32 v49, v4
	v_mov_b32_e32 v50, v4
	v_mov_b32_e32 v51, v4
	v_mov_b32_e32 v60, v4
	v_mov_b32_e32 v61, v4
	v_mov_b32_e32 v62, v4
	v_mov_b32_e32 v63, v4
	v_mov_b32_e32 v64, v4
	v_mov_b32_e32 v65, v4
	v_mov_b32_e32 v66, v4
	v_mov_b32_e32 v67, v4
	v_mov_b32_e32 v68, v4
	v_mov_b32_e32 v69, v4
	v_mov_b32_e32 v70, v4
	v_mov_b32_e32 v71, v4
	v_mov_b32_e32 v72, v4
	v_mov_b32_e32 v73, v4
	v_mov_b32_e32 v74, v4
	v_mov_b32_e32 v75, v4
	v_mov_b32_e32 v84, v4
	v_mov_b32_e32 v85, v4
	v_mov_b32_e32 v86, v4
	v_mov_b32_e32 v87, v4
	v_mov_b32_e32 v88, v4
	v_mov_b32_e32 v89, v4
	v_mov_b32_e32 v90, v4
	v_mov_b32_e32 v91, v4
	v_mov_b32_e32 v100, v4
	v_mov_b32_e32 v101, v4
	v_mov_b32_e32 v102, v4
	v_mov_b32_e32 v103, v4
	v_mov_b32_e32 v104, v4
	v_mov_b32_e32 v105, v4
	v_mov_b32_e32 v106, v4
	v_mov_b32_e32 v107, v4
	v_mov_b32_e32 v116, v4
	v_mov_b32_e32 v117, v4
	v_mov_b32_e32 v118, v4
	v_mov_b32_e32 v119, v4
	v_mov_b32_e32 v120, v4
	v_mov_b32_e32 v121, v4
	v_mov_b32_e32 v122, v4
	v_mov_b32_e32 v123, v4
	v_mov_b32_e32 v76, v4
	v_mov_b32_e32 v77, v4
	v_mov_b32_e32 v78, v4
	v_mov_b32_e32 v79, v4
	v_mov_b32_e32 v80, v4
	v_mov_b32_e32 v81, v4
	v_mov_b32_e32 v82, v4
	v_mov_b32_e32 v83, v4
	v_mov_b32_e32 v92, v4
	v_mov_b32_e32 v93, v4
	v_mov_b32_e32 v94, v4
	v_mov_b32_e32 v95, v4
	v_mov_b32_e32 v96, v4
	v_mov_b32_e32 v97, v4
	v_mov_b32_e32 v98, v4
	v_mov_b32_e32 v99, v4
	v_mov_b32_e32 v108, v4
	v_mov_b32_e32 v109, v4
	v_mov_b32_e32 v110, v4
	v_mov_b32_e32 v111, v4
	v_mov_b32_e32 v112, v4
	v_mov_b32_e32 v113, v4
	v_mov_b32_e32 v114, v4
	v_mov_b32_e32 v115, v4
	v_mov_b32_e32 v128, v4
	v_mov_b32_e32 v129, v4
	v_mov_b32_e32 v130, v4
	v_mov_b32_e32 v131, v4
	v_mov_b32_e32 v124, v4
	v_mov_b32_e32 v125, v4
	v_mov_b32_e32 v126, v4
	v_mov_b32_e32 v127, v4
	.p2alignl 6, 3212836864

.LBB0_2889:
	v_lshlrev_b32_e32 v19, 1, v17
	v_lshlrev_b32_e32 v20, 5, v17
	s_lshl_b32 s14, s14, 5
	v_lshlrev_b32_e32 v21, 6, v17
	v_lshlrev_b32_e32 v17, 2, v17
	s_add_i32 s20, s16, 0x18000
	v_and_b32_e32 v19, 32, v19
	s_and_b32 s41, s14, 0x60
	v_and_b32_e32 v21, 0x3c0, v21
	v_and_b32_e32 v17, 32, v17
	s_add_i32 s42, s20, s13
	s_lshl_b32 s35, s12, 6
	v_and_b32_e32 v20, 0x400, v20
	s_lshl_b32 s14, s41, 7
	v_bitop3_b32 v17, v21, v17, v19 bitop3:0x36
	s_lshl_b32 s12, s12, 13
	v_lshl_add_u64 v[10:11], v[10:11], 0, s[64:65]
	s_mov_b32 m0, s42
	s_add_i32 s43, s42, 0x2000
	s_add_i32 s44, s37, 0x8000
	s_add_i32 s45, s37, 0xa000
	v_or3_b32 v184, s14, v17, v20
	s_waitcnt vmcnt(2)
	s_barrier
	global_load_lds_dwordx4 v[10:11], off
	v_lshl_add_u64 v[8:9], v[8:9], 0, s[64:65]
	s_mov_b32 m0, s43
	s_add_u32 s14, s2, 0x40080
	global_load_lds_dwordx4 v[8:9], off
	v_lshl_add_u64 v[6:7], v[6:7], 0, s[64:65]
	s_mov_b32 m0, s44
	s_addc_u32 s15, s3, 0
	s_add_i32 s21, s16, 0x1c000
	global_load_lds_dwordx4 v[6:7], off
	v_lshl_add_u64 v[4:5], v[4:5], 0, s[64:65]
	s_mov_b32 m0, s45
	s_add_i32 s46, s21, s13
	global_load_lds_dwordx4 v[4:5], off
	v_lshl_add_u64 v[4:5], s[14:15], 0, v[2:3]
	s_mov_b32 m0, s46
	s_add_i32 s47, s46, 0x2000
	global_load_lds_dwordx4 v[4:5], off
	v_lshl_add_u64 v[4:5], s[14:15], 0, v[168:169]
	s_mov_b32 m0, s47
	v_or3_b32 v19, v17, s12, v20
	global_load_lds_dwordx4 v[4:5], off
	v_readlane_b32 s12, v254, 38
	v_lshlrev_b32_e32 v4, 14, v12
	s_add_u32 s48, s8, s12
	v_and_b32_e32 v4, 0xffff8000, v4
	s_addc_u32 s49, s9, 0
	v_readlane_b32 s12, v254, 39
	v_lshl_add_u32 v4, v13, 11, v4
	v_and_b32_e32 v5, 1, v12
	s_add_u32 s12, s8, s12
	v_readlane_b32 s13, v254, 40
	v_lshl_or_b32 v4, v5, 6, v4
	s_addc_u32 s13, s9, s13
	v_lshl_add_u32 v4, v14, 1, v4
	v_mov_b32_e32 v5, v3
	v_lshl_add_u64 v[170:171], s[12:13], 0, v[4:5]
	v_lshlrev_b32_e32 v4, 14, v15
	v_and_b32_e32 v4, 0xffff8000, v4
	v_lshl_add_u32 v4, v16, 11, v4
	v_and_b32_e32 v5, 1, v15
	v_lshl_or_b32 v4, v5, 6, v4
	v_lshl_add_u32 v4, v18, 1, v4
	v_mov_b32_e32 v5, v3
	s_waitcnt vmcnt(6)
	v_lshl_add_u64 v[172:173], s[12:13], 0, v[4:5]
	v_readlane_b32 s12, v254, 41
	s_add_u32 s50, s8, s12
	v_readlane_b32 s12, v254, 44
	v_mov_b32_e32 v36, 0
	s_addc_u32 s51, s9, s12
	s_mov_b32 s52, -2
	s_mov_b64 s[12:13], 0
	v_add_u32_e32 v185, s16, v19
	v_mov_b32_e32 v37, v36
	v_mov_b32_e32 v38, v36
	v_mov_b32_e32 v39, v36
	v_mov_b32_e32 v40, v36
	v_mov_b32_e32 v41, v36
	v_mov_b32_e32 v42, v36
	v_mov_b32_e32 v43, v36
	v_mov_b32_e32 v52, v36
	v_mov_b32_e32 v53, v36
	v_mov_b32_e32 v54, v36
	v_mov_b32_e32 v55, v36
	v_mov_b32_e32 v56, v36
	v_mov_b32_e32 v57, v36
	v_mov_b32_e32 v58, v36
	v_mov_b32_e32 v59, v36
	v_mov_b32_e32 v68, v36
	v_mov_b32_e32 v69, v36
	v_mov_b32_e32 v70, v36
	v_mov_b32_e32 v71, v36
	v_mov_b32_e32 v72, v36
	v_mov_b32_e32 v73, v36
	v_mov_b32_e32 v74, v36
	v_mov_b32_e32 v75, v36
	v_mov_b32_e32 v84, v36
	v_mov_b32_e32 v85, v36
	v_mov_b32_e32 v86, v36
	v_mov_b32_e32 v87, v36
	v_mov_b32_e32 v88, v36
	v_mov_b32_e32 v89, v36
	v_mov_b32_e32 v90, v36
	v_mov_b32_e32 v91, v36
	v_mov_b32_e32 v44, v36
	v_mov_b32_e32 v45, v36
	v_mov_b32_e32 v46, v36
	v_mov_b32_e32 v47, v36
	v_mov_b32_e32 v48, v36
	v_mov_b32_e32 v49, v36
	v_mov_b32_e32 v50, v36
	v_mov_b32_e32 v51, v36
	v_mov_b32_e32 v60, v36
	v_mov_b32_e32 v61, v36
	v_mov_b32_e32 v62, v36
	v_mov_b32_e32 v63, v36
	v_mov_b32_e32 v64, v36
	v_mov_b32_e32 v65, v36
	v_mov_b32_e32 v66, v36
	v_mov_b32_e32 v67, v36
	v_mov_b32_e32 v76, v36
	v_mov_b32_e32 v77, v36
	v_mov_b32_e32 v78, v36
	v_mov_b32_e32 v79, v36
	v_mov_b32_e32 v80, v36
	v_mov_b32_e32 v81, v36
	v_mov_b32_e32 v82, v36
	v_mov_b32_e32 v83, v36
	v_mov_b32_e32 v92, v36
	v_mov_b32_e32 v93, v36
	v_mov_b32_e32 v94, v36
	v_mov_b32_e32 v95, v36
	v_mov_b32_e32 v96, v36
	v_mov_b32_e32 v97, v36
	v_mov_b32_e32 v98, v36
	v_mov_b32_e32 v99, v36
	v_mov_b32_e32 v100, v36
	v_mov_b32_e32 v101, v36
	v_mov_b32_e32 v102, v36
	v_mov_b32_e32 v103, v36
	v_mov_b32_e32 v104, v36
	v_mov_b32_e32 v105, v36
	v_mov_b32_e32 v106, v36
	v_mov_b32_e32 v107, v36
	v_mov_b32_e32 v116, v36
	v_mov_b32_e32 v117, v36
	v_mov_b32_e32 v118, v36
	v_mov_b32_e32 v119, v36
	v_mov_b32_e32 v120, v36
	v_mov_b32_e32 v121, v36
	v_mov_b32_e32 v122, v36
	v_mov_b32_e32 v123, v36
	v_mov_b32_e32 v132, v36
	v_mov_b32_e32 v133, v36
	v_mov_b32_e32 v134, v36
	v_mov_b32_e32 v135, v36
	v_mov_b32_e32 v136, v36
	v_mov_b32_e32 v137, v36
	v_mov_b32_e32 v138, v36
	v_mov_b32_e32 v139, v36
	v_mov_b32_e32 v148, v36
	v_mov_b32_e32 v149, v36
	v_mov_b32_e32 v150, v36
	v_mov_b32_e32 v151, v36
	v_mov_b32_e32 v152, v36
	v_mov_b32_e32 v153, v36
	v_mov_b32_e32 v154, v36
	v_mov_b32_e32 v155, v36
	v_mov_b32_e32 v108, v36
	v_mov_b32_e32 v109, v36
	v_mov_b32_e32 v110, v36
	v_mov_b32_e32 v111, v36
	v_mov_b32_e32 v112, v36
	v_mov_b32_e32 v113, v36
	v_mov_b32_e32 v114, v36
	v_mov_b32_e32 v115, v36
	v_mov_b32_e32 v124, v36
	v_mov_b32_e32 v125, v36
	v_mov_b32_e32 v126, v36
	v_mov_b32_e32 v127, v36
	v_mov_b32_e32 v128, v36
	v_mov_b32_e32 v129, v36
	v_mov_b32_e32 v130, v36
	v_mov_b32_e32 v131, v36
	v_mov_b32_e32 v140, v36
	v_mov_b32_e32 v141, v36
	v_mov_b32_e32 v142, v36
	v_mov_b32_e32 v143, v36
	v_mov_b32_e32 v144, v36
	v_mov_b32_e32 v145, v36
	v_mov_b32_e32 v146, v36
	v_mov_b32_e32 v147, v36
	v_mov_b32_e32 v156, v36
	v_mov_b32_e32 v157, v36
	v_mov_b32_e32 v158, v36
	v_mov_b32_e32 v159, v36
	v_mov_b32_e32 v160, v36
	v_mov_b32_e32 v161, v36
	v_mov_b32_e32 v162, v36
	v_mov_b32_e32 v163, v36
	s_barrier
	.p2alignl 6, 3212836864

.LBB0_2895:
	s_lshl_b32 s14, s14, 5
	s_add_i32 s40, s20, s13
	v_and_b32_e32 v19, 48, v17
	v_lshlrev_b32_e32 v20, 6, v17
	s_movk_i32 s15, 0x3c0
	v_lshlrev_b32_e32 v17, 2, v17
	s_and_b32 s39, s14, 0x60
	v_lshl_add_u64 v[8:9], v[8:9], 0, s[64:65]
	s_mov_b32 m0, s40
	s_add_i32 s41, s40, 0x2000
	s_lshl_b32 s34, s12, 6
	v_and_or_b32 v19, v20, s15, v19
	v_and_b32_e32 v17, 32, v17
	s_lshl_b32 s12, s12, 13
	s_lshl_b32 s14, s39, 7
	s_waitcnt vmcnt(2)
	s_barrier
	global_load_lds_dwordx4 v[8:9], off
	v_lshl_add_u64 v[6:7], v[6:7], 0, s[64:65]
	s_mov_b32 m0, s41
	s_add_i32 s42, s27, 0x8000
	s_add_i32 s43, s27, 0xa000
	v_bitop3_b32 v126, s14, v19, v17 bitop3:0xf6
	global_load_lds_dwordx4 v[6:7], off
	v_lshl_add_u64 v[4:5], v[4:5], 0, s[64:65]
	s_mov_b32 m0, s42
	s_add_u32 s14, s2, 0x80080
	global_load_lds_dwordx4 v[4:5], off
	v_lshl_add_u64 v[4:5], v[10:11], 0, s[64:65]
	s_mov_b32 m0, s43
	s_addc_u32 s15, s3, 0
	s_add_i32 s44, s21, s13
	global_load_lds_dwordx4 v[4:5], off
	v_lshl_add_u64 v[4:5], s[14:15], 0, v[2:3]
	s_mov_b32 m0, s44
	s_add_i32 s45, s44, 0x2000
	global_load_lds_dwordx4 v[4:5], off
	v_lshl_add_u64 v[4:5], s[14:15], 0, v[120:121]
	s_mov_b32 m0, s45
	v_bitop3_b32 v17, v19, s12, v17 bitop3:0xde
	global_load_lds_dwordx4 v[4:5], off
	v_readlane_b32 s12, v254, 48
	v_lshlrev_b32_e32 v4, 15, v12
	s_add_u32 s46, s8, s12
	v_and_b32_e32 v4, 0xffff0000, v4
	s_addc_u32 s47, s9, 0
	v_readlane_b32 s12, v254, 49
	v_lshl_add_u32 v4, v13, 12, v4
	v_and_b32_e32 v5, 1, v12
	s_add_u32 s12, s8, s12
	v_readlane_b32 s13, v254, 50
	v_lshl_or_b32 v4, v5, 6, v4
	s_addc_u32 s13, s9, s13
	v_lshl_add_u32 v4, v14, 1, v4
	v_mov_b32_e32 v5, v3
	v_lshl_add_u64 v[122:123], s[12:13], 0, v[4:5]
	v_lshlrev_b32_e32 v4, 15, v15
	v_and_b32_e32 v4, 0xffff0000, v4
	v_lshl_add_u32 v4, v16, 12, v4
	v_and_b32_e32 v5, 1, v15
	v_lshl_or_b32 v4, v5, 6, v4
	v_lshl_add_u32 v4, v18, 1, v4
	v_mov_b32_e32 v5, v3
	s_waitcnt vmcnt(6)
	v_lshl_add_u64 v[124:125], s[12:13], 0, v[4:5]
	v_readlane_b32 s12, v254, 51
	s_add_u32 s48, s8, s12
	v_readlane_b32 s8, v254, 54
	v_mov_b32_e32 v4, 0
	s_addc_u32 s49, s9, s8
	s_mov_b32 s50, -2
	s_mov_b64 s[8:9], 0
	v_add_u32_e32 v127, s16, v17
	v_mov_b32_e32 v5, v4
	v_mov_b32_e32 v6, v4
	v_mov_b32_e32 v7, v4
	v_mov_b32_e32 v8, v4
	v_mov_b32_e32 v9, v4
	v_mov_b32_e32 v10, v4
	v_mov_b32_e32 v11, v4
	v_mov_b32_e32 v20, v4
	v_mov_b32_e32 v21, v4
	v_mov_b32_e32 v22, v4
	v_mov_b32_e32 v23, v4
	v_mov_b32_e32 v24, v4
	v_mov_b32_e32 v25, v4
	v_mov_b32_e32 v26, v4
	v_mov_b32_e32 v27, v4
	v_mov_b32_e32 v36, v4
	v_mov_b32_e32 v37, v4
	v_mov_b32_e32 v38, v4
	v_mov_b32_e32 v39, v4
	v_mov_b32_e32 v40, v4
	v_mov_b32_e32 v41, v4
	v_mov_b32_e32 v42, v4
	v_mov_b32_e32 v43, v4
	v_mov_b32_e32 v52, v4
	v_mov_b32_e32 v53, v4
	v_mov_b32_e32 v54, v4
	v_mov_b32_e32 v55, v4
	v_mov_b32_e32 v56, v4
	v_mov_b32_e32 v57, v4
	v_mov_b32_e32 v58, v4
	v_mov_b32_e32 v59, v4
	v_mov_b32_e32 v12, v4
	v_mov_b32_e32 v13, v4
	v_mov_b32_e32 v14, v4
	v_mov_b32_e32 v15, v4
	v_mov_b32_e32 v16, v4
	v_mov_b32_e32 v17, v4
	v_mov_b32_e32 v18, v4
	v_mov_b32_e32 v19, v4
	v_mov_b32_e32 v28, v4
	v_mov_b32_e32 v29, v4
	v_mov_b32_e32 v30, v4
	v_mov_b32_e32 v31, v4
	v_mov_b32_e32 v32, v4
	v_mov_b32_e32 v33, v4
	v_mov_b32_e32 v34, v4
	v_mov_b32_e32 v35, v4
	v_mov_b32_e32 v44, v4
	v_mov_b32_e32 v45, v4
	v_mov_b32_e32 v46, v4
	v_mov_b32_e32 v47, v4
	v_mov_b32_e32 v48, v4
	v_mov_b32_e32 v49, v4
	v_mov_b32_e32 v50, v4
	v_mov_b32_e32 v51, v4
	v_mov_b32_e32 v60, v4
	v_mov_b32_e32 v61, v4
	v_mov_b32_e32 v62, v4
	v_mov_b32_e32 v63, v4
	v_mov_b32_e32 v64, v4
	v_mov_b32_e32 v65, v4
	v_mov_b32_e32 v66, v4
	v_mov_b32_e32 v67, v4
	v_mov_b32_e32 v68, v4
	v_mov_b32_e32 v69, v4
	v_mov_b32_e32 v70, v4
	v_mov_b32_e32 v71, v4
	v_mov_b32_e32 v72, v4
	v_mov_b32_e32 v73, v4
	v_mov_b32_e32 v74, v4
	v_mov_b32_e32 v75, v4
	v_mov_b32_e32 v84, v4
	v_mov_b32_e32 v85, v4
	v_mov_b32_e32 v86, v4
	v_mov_b32_e32 v87, v4
	v_mov_b32_e32 v88, v4
	v_mov_b32_e32 v89, v4
	v_mov_b32_e32 v90, v4
	v_mov_b32_e32 v91, v4
	v_mov_b32_e32 v100, v4
	v_mov_b32_e32 v101, v4
	v_mov_b32_e32 v102, v4
	v_mov_b32_e32 v103, v4
	v_mov_b32_e32 v104, v4
	v_mov_b32_e32 v105, v4
	v_mov_b32_e32 v106, v4
	v_mov_b32_e32 v107, v4
	v_mov_b32_e32 v136, v4
	v_mov_b32_e32 v137, v4
	v_mov_b32_e32 v138, v4
	v_mov_b32_e32 v139, v4
	v_mov_b32_e32 v144, v4
	v_mov_b32_e32 v145, v4
	v_mov_b32_e32 v146, v4
	v_mov_b32_e32 v147, v4
	v_mov_b32_e32 v76, v4
	v_mov_b32_e32 v77, v4
	v_mov_b32_e32 v78, v4
	v_mov_b32_e32 v79, v4
	v_mov_b32_e32 v80, v4
	v_mov_b32_e32 v81, v4
	v_mov_b32_e32 v82, v4
	v_mov_b32_e32 v83, v4
	v_mov_b32_e32 v92, v4
	v_mov_b32_e32 v93, v4
	v_mov_b32_e32 v94, v4
	v_mov_b32_e32 v95, v4
	v_mov_b32_e32 v96, v4
	v_mov_b32_e32 v97, v4
	v_mov_b32_e32 v98, v4
	v_mov_b32_e32 v99, v4
	v_mov_b32_e32 v108, v4
	v_mov_b32_e32 v109, v4
	v_mov_b32_e32 v110, v4
	v_mov_b32_e32 v111, v4
	v_mov_b32_e32 v112, v4
	v_mov_b32_e32 v113, v4
	v_mov_b32_e32 v114, v4
	v_mov_b32_e32 v115, v4
	v_mov_b32_e32 v152, v4
	v_mov_b32_e32 v153, v4
	v_mov_b32_e32 v154, v4
	v_mov_b32_e32 v155, v4
	v_mov_b32_e32 v156, v4
	v_mov_b32_e32 v157, v4
	v_mov_b32_e32 v158, v4
	v_mov_b32_e32 v159, v4
	s_barrier
	.p2alignl 6, 3212836864

.LBB0_3115:
	s_ashr_i32 s13, s12, 31
	s_lshl_b64 s[14:15], s[12:13], 20
	s_add_u32 s14, s20, s14
	s_addc_u32 s15, s21, s15
	s_and_b64 s[18:19], s[2:3], exec
	s_cselect_b32 s13, s15, s35
	s_cselect_b32 s69, s14, s34
	s_ashr_i32 s11, s10, 31
	s_lshl_b64 s[18:19], s[10:11], 20
	s_add_u32 s24, s22, s18
	s_addc_u32 s25, s23, s19
	s_and_b64 s[18:19], s[2:3], exec
	s_cselect_b32 s11, s25, s39
	s_cselect_b32 s70, s24, s38
	s_add_u32 s34, s34, 0x80080
	s_addc_u32 s35, s35, 0
	s_add_u32 s71, s38, 0x100
	v_mov_b32_e32 v4, 0
	s_addc_u32 s73, s39, 0
	s_mov_b32 s74, -2
	v_mov_b32_e32 v5, v4
	v_mov_b32_e32 v6, v4
	v_mov_b32_e32 v7, v4
	v_mov_b32_e32 v12, v4
	v_mov_b32_e32 v13, v4
	v_mov_b32_e32 v14, v4
	v_mov_b32_e32 v15, v4
	v_mov_b32_e32 v20, v4
	v_mov_b32_e32 v21, v4
	v_mov_b32_e32 v22, v4
	v_mov_b32_e32 v23, v4
	v_mov_b32_e32 v28, v4
	v_mov_b32_e32 v29, v4
	v_mov_b32_e32 v30, v4
	v_mov_b32_e32 v31, v4
	v_mov_b32_e32 v36, v4
	v_mov_b32_e32 v37, v4
	v_mov_b32_e32 v38, v4
	v_mov_b32_e32 v39, v4
	v_mov_b32_e32 v44, v4
	v_mov_b32_e32 v45, v4
	v_mov_b32_e32 v46, v4
	v_mov_b32_e32 v47, v4
	v_mov_b32_e32 v52, v4
	v_mov_b32_e32 v53, v4
	v_mov_b32_e32 v54, v4
	v_mov_b32_e32 v55, v4
	v_mov_b32_e32 v60, v4
	v_mov_b32_e32 v61, v4
	v_mov_b32_e32 v62, v4
	v_mov_b32_e32 v63, v4
	v_mov_b32_e32 v8, v4
	v_mov_b32_e32 v9, v4
	v_mov_b32_e32 v10, v4
	v_mov_b32_e32 v11, v4
	v_mov_b32_e32 v16, v4
	v_mov_b32_e32 v17, v4
	v_mov_b32_e32 v18, v4
	v_mov_b32_e32 v19, v4
	v_mov_b32_e32 v24, v4
	v_mov_b32_e32 v25, v4
	v_mov_b32_e32 v26, v4
	v_mov_b32_e32 v27, v4
	v_mov_b32_e32 v32, v4
	v_mov_b32_e32 v33, v4
	v_mov_b32_e32 v34, v4
	v_mov_b32_e32 v35, v4
	v_mov_b32_e32 v40, v4
	v_mov_b32_e32 v41, v4
	v_mov_b32_e32 v42, v4
	v_mov_b32_e32 v43, v4
	v_mov_b32_e32 v48, v4
	v_mov_b32_e32 v49, v4
	v_mov_b32_e32 v50, v4
	v_mov_b32_e32 v51, v4
	v_mov_b32_e32 v56, v4
	v_mov_b32_e32 v57, v4
	v_mov_b32_e32 v58, v4
	v_mov_b32_e32 v59, v4
	v_mov_b32_e32 v64, v4
	v_mov_b32_e32 v65, v4
	v_mov_b32_e32 v66, v4
	v_mov_b32_e32 v67, v4
	v_mov_b32_e32 v68, v4
	v_mov_b32_e32 v69, v4
	v_mov_b32_e32 v70, v4
	v_mov_b32_e32 v71, v4
	v_mov_b32_e32 v76, v4
	v_mov_b32_e32 v77, v4
	v_mov_b32_e32 v78, v4
	v_mov_b32_e32 v79, v4
	v_mov_b32_e32 v84, v4
	v_mov_b32_e32 v85, v4
	v_mov_b32_e32 v86, v4
	v_mov_b32_e32 v87, v4
	v_mov_b32_e32 v92, v4
	v_mov_b32_e32 v93, v4
	v_mov_b32_e32 v94, v4
	v_mov_b32_e32 v95, v4
	v_mov_b32_e32 v100, v4
	v_mov_b32_e32 v101, v4
	v_mov_b32_e32 v102, v4
	v_mov_b32_e32 v103, v4
	v_mov_b32_e32 v108, v4
	v_mov_b32_e32 v109, v4
	v_mov_b32_e32 v110, v4
	v_mov_b32_e32 v111, v4
	v_mov_b32_e32 v116, v4
	v_mov_b32_e32 v117, v4
	v_mov_b32_e32 v118, v4
	v_mov_b32_e32 v119, v4
	v_mov_b32_e32 v124, v4
	v_mov_b32_e32 v125, v4
	v_mov_b32_e32 v126, v4
	v_mov_b32_e32 v127, v4
	v_mov_b32_e32 v72, v4
	v_mov_b32_e32 v73, v4
	v_mov_b32_e32 v74, v4
	v_mov_b32_e32 v75, v4
	v_mov_b32_e32 v80, v4
	v_mov_b32_e32 v81, v4
	v_mov_b32_e32 v82, v4
	v_mov_b32_e32 v83, v4
	v_mov_b32_e32 v88, v4
	v_mov_b32_e32 v89, v4
	v_mov_b32_e32 v90, v4
	v_mov_b32_e32 v91, v4
	v_mov_b32_e32 v96, v4
	v_mov_b32_e32 v97, v4
	v_mov_b32_e32 v98, v4
	v_mov_b32_e32 v99, v4
	v_mov_b32_e32 v104, v4
	v_mov_b32_e32 v105, v4
	v_mov_b32_e32 v106, v4
	v_mov_b32_e32 v107, v4
	v_mov_b32_e32 v112, v4
	v_mov_b32_e32 v113, v4
	v_mov_b32_e32 v114, v4
	v_mov_b32_e32 v115, v4
	v_mov_b32_e32 v120, v4
	v_mov_b32_e32 v121, v4
	v_mov_b32_e32 v122, v4
	v_mov_b32_e32 v123, v4
	v_mov_b32_e32 v128, v4
	v_mov_b32_e32 v129, v4
	v_mov_b32_e32 v130, v4
	v_mov_b32_e32 v131, v4
	.p2alignl 6, 3212836864

.LBB0_3194:
	s_add_u32 s71, s24, 0x100
	v_mov_b32_e32 v4, 0
	s_addc_u32 s73, s25, 0
	s_mov_b32 s74, -2
	v_mov_b32_e32 v5, v4
	v_mov_b32_e32 v6, v4
	v_mov_b32_e32 v7, v4
	v_mov_b32_e32 v8, v4
	v_mov_b32_e32 v9, v4
	v_mov_b32_e32 v10, v4
	v_mov_b32_e32 v11, v4
	v_mov_b32_e32 v20, v4
	v_mov_b32_e32 v21, v4
	v_mov_b32_e32 v22, v4
	v_mov_b32_e32 v23, v4
	v_mov_b32_e32 v24, v4
	v_mov_b32_e32 v25, v4
	v_mov_b32_e32 v26, v4
	v_mov_b32_e32 v27, v4
	v_mov_b32_e32 v36, v4
	v_mov_b32_e32 v37, v4
	v_mov_b32_e32 v38, v4
	v_mov_b32_e32 v39, v4
	v_mov_b32_e32 v40, v4
	v_mov_b32_e32 v41, v4
	v_mov_b32_e32 v42, v4
	v_mov_b32_e32 v43, v4
	v_mov_b32_e32 v52, v4
	v_mov_b32_e32 v53, v4
	v_mov_b32_e32 v54, v4
	v_mov_b32_e32 v55, v4
	v_mov_b32_e32 v56, v4
	v_mov_b32_e32 v57, v4
	v_mov_b32_e32 v58, v4
	v_mov_b32_e32 v59, v4
	v_mov_b32_e32 v12, v4
	v_mov_b32_e32 v13, v4
	v_mov_b32_e32 v14, v4
	v_mov_b32_e32 v15, v4
	v_mov_b32_e32 v16, v4
	v_mov_b32_e32 v17, v4
	v_mov_b32_e32 v18, v4
	v_mov_b32_e32 v19, v4
	v_mov_b32_e32 v28, v4
	v_mov_b32_e32 v29, v4
	v_mov_b32_e32 v30, v4
	v_mov_b32_e32 v31, v4
	v_mov_b32_e32 v32, v4
	v_mov_b32_e32 v33, v4
	v_mov_b32_e32 v34, v4
	v_mov_b32_e32 v35, v4
	v_mov_b32_e32 v44, v4
	v_mov_b32_e32 v45, v4
	v_mov_b32_e32 v46, v4
	v_mov_b32_e32 v47, v4
	v_mov_b32_e32 v48, v4
	v_mov_b32_e32 v49, v4
	v_mov_b32_e32 v50, v4
	v_mov_b32_e32 v51, v4
	v_mov_b32_e32 v60, v4
	v_mov_b32_e32 v61, v4
	v_mov_b32_e32 v62, v4
	v_mov_b32_e32 v63, v4
	v_mov_b32_e32 v64, v4
	v_mov_b32_e32 v65, v4
	v_mov_b32_e32 v66, v4
	v_mov_b32_e32 v67, v4
	v_mov_b32_e32 v68, v4
	v_mov_b32_e32 v69, v4
	v_mov_b32_e32 v70, v4
	v_mov_b32_e32 v71, v4
	v_mov_b32_e32 v72, v4
	v_mov_b32_e32 v73, v4
	v_mov_b32_e32 v74, v4
	v_mov_b32_e32 v75, v4
	v_mov_b32_e32 v84, v4
	v_mov_b32_e32 v85, v4
	v_mov_b32_e32 v86, v4
	v_mov_b32_e32 v87, v4
	v_mov_b32_e32 v88, v4
	v_mov_b32_e32 v89, v4
	v_mov_b32_e32 v90, v4
	v_mov_b32_e32 v91, v4
	v_mov_b32_e32 v100, v4
	v_mov_b32_e32 v101, v4
	v_mov_b32_e32 v102, v4
	v_mov_b32_e32 v103, v4
	v_mov_b32_e32 v104, v4
	v_mov_b32_e32 v105, v4
	v_mov_b32_e32 v106, v4
	v_mov_b32_e32 v107, v4
	v_mov_b32_e32 v116, v4
	v_mov_b32_e32 v117, v4
	v_mov_b32_e32 v118, v4
	v_mov_b32_e32 v119, v4
	v_mov_b32_e32 v120, v4
	v_mov_b32_e32 v121, v4
	v_mov_b32_e32 v122, v4
	v_mov_b32_e32 v123, v4
	v_mov_b32_e32 v76, v4
	v_mov_b32_e32 v77, v4
	v_mov_b32_e32 v78, v4
	v_mov_b32_e32 v79, v4
	v_mov_b32_e32 v80, v4
	v_mov_b32_e32 v81, v4
	v_mov_b32_e32 v82, v4
	v_mov_b32_e32 v83, v4
	v_mov_b32_e32 v92, v4
	v_mov_b32_e32 v93, v4
	v_mov_b32_e32 v94, v4
	v_mov_b32_e32 v95, v4
	v_mov_b32_e32 v96, v4
	v_mov_b32_e32 v97, v4
	v_mov_b32_e32 v98, v4
	v_mov_b32_e32 v99, v4
	v_mov_b32_e32 v108, v4
	v_mov_b32_e32 v109, v4
	v_mov_b32_e32 v110, v4
	v_mov_b32_e32 v111, v4
	v_mov_b32_e32 v112, v4
	v_mov_b32_e32 v113, v4
	v_mov_b32_e32 v114, v4
	v_mov_b32_e32 v115, v4
	v_mov_b32_e32 v124, v4
	v_mov_b32_e32 v125, v4
	v_mov_b32_e32 v126, v4
	v_mov_b32_e32 v127, v4
	v_mov_b32_e32 v128, v4
	v_mov_b32_e32 v129, v4
	v_mov_b32_e32 v130, v4
	v_mov_b32_e32 v131, v4
	.p2alignl 6, 3212836864
